# G2 inner loop rewritten by hand: compute waves issue no DMA, helper waves stream all 56 pieces, u/eg loads by SGPR base, single loop body
# speedup vs baseline: 1.0138x; 1.0094x over previous
.LBB0_563:
	v_lshlrev_b32_e32 v252, 4, v58
	s_and_b64 vcc, exec, s[6:7]
	s_cbranch_vccz .Lg2h_setup
	s_lshl_b32 s4, s83, 11
	s_add_u32 s28, s28, s4
	s_addc_u32 s29, s29, 0
	s_add_u32 s48, s92, s46
	s_addc_u32 s49, s93, s47
	s_lshl_b32 s4, s78, 3
	s_add_u32 s48, s48, s4
	s_addc_u32 s49, s49, 0
	s_add_u32 s48, s48, 0xdd20000
	s_addc_u32 s49, s49, 0
	s_add_u32 s36, s92, s36
	s_addc_u32 s37, s93, s37
	s_add_u32 s36, s36, 0x80000
	s_addc_u32 s37, s37, 0
	global_load_dword v236, v1, s[36:37]
	s_add_u32 s36, s36, 32
	s_addc_u32 s37, s37, 0
	s_mov_b32 s19, 0
	v_mov_b32_e32 v238, v252
	v_and_b32_e32 v250, 15, v58
	v_lshlrev_b32_e32 v250, 1, v250
	v_lshrrev_b32_e32 v251, 4, v58
	v_lshlrev_b32_e32 v251, 13, v251
	v_add_u32_e32 v239, v250, v251
	v_add_u32_e32 v240, 0x1000, v239
	v_add_u32_e32 v241, 0x8000, v239
	v_add_u32_e32 v242, 0x9000, v239
	v_add_u32_e32 v243, 0x10000, v239
	v_add_u32_e32 v246, 0x11000, v239
	v_add_u32_e32 v247, 0x18000, v239
	v_add_u32_e32 v248, 0x19000, v239
	v_lshlrev_b32_e32 v249, 3, v58
.Lg2c_loop:
	ds_read_b128 v[80:83], v238 offset:0
	ds_read_b128 v[84:87], v238 offset:4096
	ds_read_b128 v[88:91], v238 offset:8192
	ds_read_b128 v[92:95], v238 offset:12288
	ds_read_b128 v[96:99], v238 offset:16384
	ds_read_b128 v[100:103], v238 offset:20480
	ds_read_b128 v[104:107], v238 offset:24576
	ds_read_b128 v[108:111], v238 offset:28672
	ds_read_b128 v[112:115], v238 offset:1024
	ds_read_b128 v[116:119], v238 offset:5120
	ds_read_b128 v[120:123], v238 offset:9216
	ds_read_b128 v[124:127], v238 offset:13312
	ds_read_b128 v[128:131], v238 offset:17408
	ds_read_b128 v[132:135], v238 offset:21504
	ds_read_b128 v[136:139], v238 offset:25600
	ds_read_b128 v[140:143], v238 offset:29696
	v_cvt_pk_bf16_f32 v62, v4, v5
	v_cvt_pk_bf16_f32 v63, v6, v7
	v_cvt_pk_bf16_f32 v64, v8, v9
	v_cvt_pk_bf16_f32 v65, v10, v11
	v_cvt_pk_bf16_f32 v66, v12, v13
	v_cvt_pk_bf16_f32 v67, v14, v15
	v_cvt_pk_bf16_f32 v68, v16, v17
	v_cvt_pk_bf16_f32 v69, v18, v19
	v_cvt_pk_bf16_f32 v70, v20, v21
	v_cvt_pk_bf16_f32 v71, v22, v23
	v_cvt_pk_bf16_f32 v72, v24, v25
	v_cvt_pk_bf16_f32 v73, v26, v27
	v_cvt_pk_bf16_f32 v74, v28, v29
	v_cvt_pk_bf16_f32 v75, v30, v31
	v_cvt_pk_bf16_f32 v76, v32, v33
	v_cvt_pk_bf16_f32 v77, v34, v35
	s_waitcnt lgkmcnt(8)
	s_nop 1
	v_mfma_f32_16x16x32_bf16 v[176:179], v[80:83], v[62:65], 0
	v_mfma_f32_16x16x32_bf16 v[196:199], v[96:99], v[62:65], 0
	v_mfma_f32_16x16x32_bf16 v[180:183], v[84:87], v[62:65], 0
	v_mfma_f32_16x16x32_bf16 v[200:203], v[100:103], v[62:65], 0
	v_mfma_f32_16x16x32_bf16 v[184:187], v[88:91], v[62:65], 0
	v_mfma_f32_16x16x32_bf16 v[204:207], v[104:107], v[62:65], 0
	v_mfma_f32_16x16x32_bf16 v[188:191], v[92:95], v[62:65], 0
	v_mfma_f32_16x16x32_bf16 v[208:211], v[108:111], v[62:65], 0
	ds_read_b128 v[144:147], v238 offset:2048
	ds_read_b128 v[148:151], v238 offset:6144
	ds_read_b128 v[152:155], v238 offset:10240
	ds_read_b128 v[156:159], v238 offset:14336
	ds_read_b128 v[160:163], v238 offset:18432
	ds_read_b128 v[164:167], v238 offset:22528
	ds_read_b128 v[168:171], v238 offset:26624
	ds_read_b128 v[172:175], v238 offset:30720
	s_cmp_eq_u32 s19, 0
	s_cbranch_scc0 .Lg2c_w16
	s_waitcnt vmcnt(0)
.Lg2c_w16:
	s_waitcnt vmcnt(16)
	v_lshlrev_b32_e32 v212, 16, v50
	v_and_b32_e32 v213, 0xffff0000, v50
	v_lshlrev_b32_e32 v214, 16, v51
	v_and_b32_e32 v215, 0xffff0000, v51
	v_lshlrev_b32_e32 v216, 16, v52
	v_and_b32_e32 v217, 0xffff0000, v52
	v_lshlrev_b32_e32 v218, 16, v53
	v_and_b32_e32 v219, 0xffff0000, v53
	v_lshlrev_b32_e32 v220, 16, v54
	v_and_b32_e32 v221, 0xffff0000, v54
	v_lshlrev_b32_e32 v222, 16, v55
	v_and_b32_e32 v223, 0xffff0000, v55
	v_lshlrev_b32_e32 v224, 16, v56
	v_and_b32_e32 v225, 0xffff0000, v56
	v_lshlrev_b32_e32 v226, 16, v57
	v_and_b32_e32 v227, 0xffff0000, v57
	s_waitcnt lgkmcnt(8)
	v_mfma_f32_16x16x32_bf16 v[176:179], v[112:115], v[66:69], v[176:179]
	v_mfma_f32_16x16x32_bf16 v[196:199], v[128:131], v[66:69], v[196:199]
	v_mfma_f32_16x16x32_bf16 v[180:183], v[116:119], v[66:69], v[180:183]
	v_mfma_f32_16x16x32_bf16 v[200:203], v[132:135], v[66:69], v[200:203]
	v_mfma_f32_16x16x32_bf16 v[184:187], v[120:123], v[66:69], v[184:187]
	v_mfma_f32_16x16x32_bf16 v[204:207], v[136:139], v[66:69], v[204:207]
	v_mfma_f32_16x16x32_bf16 v[188:191], v[124:127], v[66:69], v[188:191]
	v_mfma_f32_16x16x32_bf16 v[208:211], v[140:143], v[66:69], v[208:211]
	ds_read_b128 v[80:83], v238 offset:3072
	ds_read_b128 v[84:87], v238 offset:7168
	ds_read_b128 v[88:91], v238 offset:11264
	ds_read_b128 v[92:95], v238 offset:15360
	ds_read_b128 v[96:99], v238 offset:19456
	ds_read_b128 v[100:103], v238 offset:23552
	ds_read_b128 v[104:107], v238 offset:27648
	ds_read_b128 v[108:111], v238 offset:31744
	v_pk_mul_f32 v[4:5], v[4:5], v[236:237] op_sel_hi:[1,0]
	v_pk_mul_f32 v[6:7], v[6:7], v[236:237] op_sel_hi:[1,0]
	v_pk_mul_f32 v[8:9], v[8:9], v[236:237] op_sel_hi:[1,0]
	v_pk_mul_f32 v[10:11], v[10:11], v[236:237] op_sel_hi:[1,0]
	v_pk_mul_f32 v[12:13], v[12:13], v[236:237] op_sel_hi:[1,0]
	v_pk_mul_f32 v[14:15], v[14:15], v[236:237] op_sel_hi:[1,0]
	v_pk_mul_f32 v[16:17], v[16:17], v[236:237] op_sel_hi:[1,0]
	v_pk_mul_f32 v[18:19], v[18:19], v[236:237] op_sel_hi:[1,0]
	v_pk_mul_f32 v[20:21], v[20:21], v[236:237] op_sel_hi:[1,0]
	v_pk_mul_f32 v[22:23], v[22:23], v[236:237] op_sel_hi:[1,0]
	v_pk_mul_f32 v[24:25], v[24:25], v[236:237] op_sel_hi:[1,0]
	v_pk_mul_f32 v[26:27], v[26:27], v[236:237] op_sel_hi:[1,0]
	v_pk_mul_f32 v[28:29], v[28:29], v[236:237] op_sel_hi:[1,0]
	v_pk_mul_f32 v[30:31], v[30:31], v[236:237] op_sel_hi:[1,0]
	v_pk_mul_f32 v[32:33], v[32:33], v[236:237] op_sel_hi:[1,0]
	v_pk_mul_f32 v[34:35], v[34:35], v[236:237] op_sel_hi:[1,0]
	s_cmp_lt_u32 s19, 31
	s_cbranch_scc0 .Lg2c_noload
	global_load_dword v236, v1, s[36:37]
	global_load_dwordx2 v[50:51], v249, s[48:49] offset:0
	global_load_dwordx2 v[52:53], v249, s[48:49] offset:512
	global_load_dwordx2 v[54:55], v249, s[48:49] offset:1024
	global_load_dwordx2 v[56:57], v249, s[48:49] offset:1536
.Lg2c_noload:
	s_waitcnt lgkmcnt(8)
	v_mfma_f32_16x16x32_bf16 v[176:179], v[144:147], v[70:73], v[176:179]
	v_mfma_f32_16x16x32_bf16 v[196:199], v[160:163], v[70:73], v[196:199]
	v_mfma_f32_16x16x32_bf16 v[180:183], v[148:151], v[70:73], v[180:183]
	v_mfma_f32_16x16x32_bf16 v[200:203], v[164:167], v[70:73], v[200:203]
	v_mfma_f32_16x16x32_bf16 v[184:187], v[152:155], v[70:73], v[184:187]
	v_mfma_f32_16x16x32_bf16 v[204:207], v[168:171], v[70:73], v[204:207]
	v_mfma_f32_16x16x32_bf16 v[188:191], v[156:159], v[70:73], v[188:191]
	v_mfma_f32_16x16x32_bf16 v[208:211], v[172:175], v[70:73], v[208:211]
	ds_read_b128 v[112:115], v238 offset:32768
	ds_read_b128 v[116:119], v238 offset:34816
	ds_read_b128 v[120:123], v238 offset:36864
	ds_read_b128 v[124:127], v238 offset:38912
	ds_read_b128 v[128:131], v238 offset:40960
	ds_read_b128 v[132:135], v238 offset:43008
	ds_read_b128 v[136:139], v238 offset:45056
	ds_read_b128 v[140:143], v238 offset:47104
	s_waitcnt lgkmcnt(8)
	v_mfma_f32_16x16x32_bf16 v[176:179], v[80:83], v[74:77], v[176:179]
	v_mfma_f32_16x16x32_bf16 v[180:183], v[84:87], v[74:77], v[180:183]
	v_mfma_f32_16x16x32_bf16 v[184:187], v[88:91], v[74:77], v[184:187]
	v_mfma_f32_16x16x32_bf16 v[188:191], v[92:95], v[74:77], v[188:191]
	v_mfma_f32_16x16x32_bf16 v[196:199], v[96:99], v[74:77], v[196:199]
	v_sub_f32_e32 v212, v212, v176
	v_sub_f32_e32 v213, v213, v177
	v_sub_f32_e32 v214, v214, v178
	v_sub_f32_e32 v215, v215, v179
	v_mfma_f32_16x16x32_bf16 v[200:203], v[100:103], v[74:77], v[200:203]
	v_sub_f32_e32 v216, v216, v180
	v_sub_f32_e32 v217, v217, v181
	v_sub_f32_e32 v218, v218, v182
	v_sub_f32_e32 v219, v219, v183
	v_mfma_f32_16x16x32_bf16 v[204:207], v[104:107], v[74:77], v[204:207]
	v_sub_f32_e32 v220, v220, v184
	v_sub_f32_e32 v221, v221, v185
	v_sub_f32_e32 v222, v222, v186
	v_sub_f32_e32 v223, v223, v187
	v_mfma_f32_16x16x32_bf16 v[208:211], v[108:111], v[74:77], v[208:211]
	v_sub_f32_e32 v224, v224, v188
	v_sub_f32_e32 v225, v225, v189
	v_sub_f32_e32 v226, v226, v190
	v_sub_f32_e32 v227, v227, v191
	ds_read_b128 v[144:147], v238 offset:33792
	ds_read_b128 v[148:151], v238 offset:35840
	ds_read_b128 v[152:155], v238 offset:37888
	ds_read_b128 v[156:159], v238 offset:39936
	ds_read_b128 v[160:163], v238 offset:41984
	ds_read_b128 v[164:167], v238 offset:44032
	ds_read_b128 v[168:171], v238 offset:46080
	ds_read_b128 v[172:175], v238 offset:48128
	v_cvt_pk_bf16_f32 v228, v212, v213
	v_cvt_pk_bf16_f32 v229, v214, v215
	v_cvt_pk_bf16_f32 v230, v216, v217
	v_cvt_pk_bf16_f32 v231, v218, v219
	v_cvt_pk_bf16_f32 v232, v220, v221
	v_cvt_pk_bf16_f32 v233, v222, v223
	v_cvt_pk_bf16_f32 v234, v224, v225
	v_cvt_pk_bf16_f32 v235, v226, v227
	s_waitcnt lgkmcnt(8)
	s_nop 1
	v_mfma_f32_16x16x32_bf16 v[4:7], v[112:115], v[228:231], v[4:7]
	v_mfma_f32_16x16x32_bf16 v[8:11], v[116:119], v[228:231], v[8:11]
	v_mfma_f32_16x16x32_bf16 v[12:15], v[120:123], v[228:231], v[12:15]
	v_mfma_f32_16x16x32_bf16 v[16:19], v[124:127], v[228:231], v[16:19]
	v_mfma_f32_16x16x32_bf16 v[20:23], v[128:131], v[228:231], v[20:23]
	v_mfma_f32_16x16x32_bf16 v[24:27], v[132:135], v[228:231], v[24:27]
	v_mfma_f32_16x16x32_bf16 v[28:31], v[136:139], v[228:231], v[28:31]
	v_mfma_f32_16x16x32_bf16 v[32:35], v[140:143], v[228:231], v[32:35]
	ds_read_b128 v[80:83], v238 offset:49152
	ds_read_b128 v[84:87], v238 offset:51200
	ds_read_b128 v[88:91], v238 offset:53248
	ds_read_b128 v[92:95], v238 offset:55296
	ds_read_b128 v[96:99], v238 offset:50176
	ds_read_b128 v[100:103], v238 offset:52224
	ds_read_b128 v[104:107], v238 offset:54272
	ds_read_b128 v[108:111], v238 offset:56320
	s_waitcnt lgkmcnt(8)
	v_mfma_f32_16x16x32_bf16 v[4:7], v[144:147], v[232:235], v[4:7]
	v_mfma_f32_16x16x32_bf16 v[8:11], v[148:151], v[232:235], v[8:11]
	v_mfma_f32_16x16x32_bf16 v[12:15], v[152:155], v[232:235], v[12:15]
	v_mfma_f32_16x16x32_bf16 v[16:19], v[156:159], v[232:235], v[16:19]
	v_mfma_f32_16x16x32_bf16 v[20:23], v[160:163], v[232:235], v[20:23]
	v_mfma_f32_16x16x32_bf16 v[24:27], v[164:167], v[232:235], v[24:27]
	v_mfma_f32_16x16x32_bf16 v[28:31], v[168:171], v[232:235], v[28:31]
	v_mfma_f32_16x16x32_bf16 v[32:35], v[172:175], v[232:235], v[32:35]
	s_waitcnt lgkmcnt(0)
	v_mfma_f32_16x16x32_bf16 v[196:199], v[80:83], v[228:231], v[196:199]
	v_mfma_f32_16x16x32_bf16 v[200:203], v[84:87], v[228:231], v[200:203]
	v_mfma_f32_16x16x32_bf16 v[204:207], v[88:91], v[228:231], v[204:207]
	v_mfma_f32_16x16x32_bf16 v[208:211], v[92:95], v[228:231], v[208:211]
	v_mfma_f32_16x16x32_bf16 v[196:199], v[96:99], v[232:235], v[196:199]
	v_mfma_f32_16x16x32_bf16 v[200:203], v[100:103], v[232:235], v[200:203]
	v_mfma_f32_16x16x32_bf16 v[204:207], v[104:107], v[232:235], v[204:207]
	v_mfma_f32_16x16x32_bf16 v[208:211], v[108:111], v[232:235], v[208:211]
	s_nop 7
	s_nop 3
	v_cvt_pk_bf16_f32 v112, v196, v197
	v_cvt_pk_bf16_f32 v113, v198, v199
	v_cvt_pk_bf16_f32 v114, v200, v201
	v_cvt_pk_bf16_f32 v115, v202, v203
	v_cvt_pk_bf16_f32 v116, v204, v205
	v_cvt_pk_bf16_f32 v117, v206, v207
	v_cvt_pk_bf16_f32 v118, v208, v209
	v_cvt_pk_bf16_f32 v119, v210, v211
	global_store_short v239, v112, s[28:29]
	global_store_short_d16_hi v239, v112, s[28:29] offset:2048
	global_store_short v240, v113, s[28:29]
	global_store_short_d16_hi v240, v113, s[28:29] offset:2048
	global_store_short v241, v114, s[28:29]
	global_store_short_d16_hi v241, v114, s[28:29] offset:2048
	global_store_short v242, v115, s[28:29]
	global_store_short_d16_hi v242, v115, s[28:29] offset:2048
	global_store_short v243, v116, s[28:29]
	global_store_short_d16_hi v243, v116, s[28:29] offset:2048
	global_store_short v246, v117, s[28:29]
	global_store_short_d16_hi v246, v117, s[28:29] offset:2048
	global_store_short v247, v118, s[28:29]
	global_store_short_d16_hi v247, v118, s[28:29] offset:2048
	global_store_short v248, v119, s[28:29]
	global_store_short_d16_hi v248, v119, s[28:29] offset:2048
	s_add_u32 s28, s28, 0x20000
	s_addc_u32 s29, s29, 0
	s_add_u32 s48, s48, 0x20000
	s_addc_u32 s49, s49, 0
	s_add_u32 s36, s36, 32
	s_addc_u32 s37, s37, 0
	v_xor_b32_e32 v238, 0xe000, v238
	s_add_i32 s19, s19, 1
	s_cmp_lt_u32 s19, 32
	s_barrier
	s_cbranch_scc1 .Lg2c_loop
	s_branch .Lg2_exit
.Lg2h_setup:
	s_lshr_b32 s83, s21, 10
	s_sub_u32 s83, s83, 2
	s_lshl_b32 s79, s83, 13
	s_lshl_b32 s82, s83, 10
	v_add_u32_e32 v70, s82, v252
	v_add_u32_e32 v71, 0x1800, v70
	s_add_u32 s82, s82, 0xc000
	s_mov_b32 s78, 0xe000
	s_add_u32 s46, s92, s46
	s_addc_u32 s47, s93, s47
	s_add_u32 s46, s46, 0x6d20000
	s_addc_u32 s47, s47, 0
	s_lshr_b32 s4, s83, 1
	s_lshl_b32 s4, s4, 25
	s_add_u32 s46, s46, s4
	s_addc_u32 s47, s47, 0
	s_and_b32 s4, s83, 1
	s_lshl_b32 s4, s4, 13
	s_add_u32 s46, s46, s4
	s_addc_u32 s47, s47, 0
	s_add_u32 s42, s92, s42
	s_addc_u32 s43, s93, s43
	s_add_u32 s42, s42, 0xcd10000
	s_addc_u32 s43, s43, 0
	v_mov_b32_e32 v62, v252
	v_add_u32_e32 v63, 0x400, v252
	v_add_u32_e32 v64, 0x800, v252
	v_add_u32_e32 v65, 0xc00, v252
	v_add_u32_e32 v66, 0x1000, v252
	v_add_u32_e32 v67, 0x1400, v252
	v_add_u32_e32 v68, 0x1800, v252
	v_add_u32_e32 v69, 0x1c00, v252
	s_mov_b32 s19, 0
.Lg2h_loop:
	s_cmp_lt_u32 s19, 31
	s_cbranch_scc0 .Lg2h_nodma
	s_add_i32 s4, s79, s78
	s_mov_b32 m0, s4
	s_nop 0
	global_load_lds_dwordx4 v62, s[46:47]
	s_add_i32 m0, s4, 0x400
	s_nop 0
	global_load_lds_dwordx4 v63, s[46:47]
	s_add_i32 m0, s4, 0x800
	s_nop 0
	global_load_lds_dwordx4 v64, s[46:47]
	s_add_i32 m0, s4, 0xc00
	s_nop 0
	global_load_lds_dwordx4 v65, s[46:47]
	s_add_i32 m0, s4, 0x1000
	s_nop 0
	global_load_lds_dwordx4 v66, s[46:47]
	s_add_i32 m0, s4, 0x1400
	s_nop 0
	global_load_lds_dwordx4 v67, s[46:47]
	s_add_i32 m0, s4, 0x1800
	s_nop 0
	global_load_lds_dwordx4 v68, s[46:47]
	s_add_i32 m0, s4, 0x1c00
	s_nop 0
	global_load_lds_dwordx4 v69, s[46:47]
	s_add_i32 s4, s82, s78
	s_mov_b32 m0, s4
	s_nop 0
	global_load_lds_dwordx4 v70, s[42:43]
	s_cmp_lt_u32 s83, 2
	s_cbranch_scc0 .Lg2h_no2
	s_add_i32 m0, s4, 0x1800
	s_nop 0
	global_load_lds_dwordx4 v71, s[42:43]
.Lg2h_no2:
	s_add_u32 s46, s46, 0x20000
	s_addc_u32 s47, s47, 0
	s_add_u32 s42, s42, 0x10000
	s_addc_u32 s43, s43, 0
	s_sub_u32 s78, 0xe000, s78
.Lg2h_nodma:
	s_waitcnt vmcnt(0)
	s_add_i32 s19, s19, 1
	s_cmp_lt_u32 s19, 32
	s_barrier
	s_cbranch_scc1 .Lg2h_loop
